# combo36: combo23 + prep_tokens rope-partner exchange (lane xor 8) done with DPP row_ror:8 moves instead of four ds_bpermute LDS round trips
# speedup vs baseline: 1.0028x; 1.0028x over previous
; __device__ __forceinline__ unsigned pk2(float lo, float hi) { const f32x2 v = {lo, hi}; return __builtin_bit_cast(unsigned, __builtin_convertvector(v, hwbf16x2)); }
; __device__ __forceinline__ void prep_tokens(const bf16_t* __restrict__ proj, bf16_t* __restrict__ qn, bf16_t* __restrict__ kvn, bf16_t* __restrict__ Kb, const float* __restrict__ qa, const float* __restrict__ kva, const float* __restrict__ kr, ...
;     ...
;     for (int tg = gw; tg < T / 4; tg += NGW) { const int t = 4 * tg + sub;
;         const bf16_t* pr = proj + (size_t)t * NIN;
;         const u32x4 q0 = *(const u32x4*)(pr + 1536 + 16 * l16), q1 = *(const u32x4*)(pr + 1536 + 16 * l16 + 8);
;         const u32x4 k0 = *(const u32x4*)(pr + 1792 + 8 * l16);
;         const u32x2 p0 = *(const u32x2*)(pr + 1920 + 4 * l16);
;         const f32x4 c4 = *(const f32x4*)(cosT + (size_t)t * 32 + 4 * (l16 & 7)), s4 = *(const f32x4*)(sinT + (size_t)t * 32 + 4 * (l16 & 7));
;         { float f[16]; float ss = 0.f;
; #pragma unroll
;           for (int e2 = 0; e2 < 4; ++e2) { f[2 * e2] = __uint_as_float(q0[e2] << 16); f[2 * e2 + 1] = __uint_as_float(q0[e2] & 0xffff0000u); f[8 + 2 * e2] = __uint_as_float(q1[e2] << 16); f[8 + 2 * e2 + 1] = __uint_as_float(q1[e2] & 0xffff0000u); }
; #pragma unroll
;           for (int e2 = 0; e2 < 16; ++e2) ss += f[e2] * f[e2];
;           const float rr = __builtin_amdgcn_rsqf(sum16(ss) * (1.0f / 256.0f) + EPS);
;           u32x4 o0, o1;
; #pragma unroll
;           for (int e2 = 0; e2 < 4; ++e2) { o0[e2] = pk2(f[2 * e2] * rr * gq[e2 >> 1][2 * (e2 & 1)], f[2 * e2 + 1] * rr * gq[e2 >> 1][2 * (e2 & 1) + 1]);
;                                            o1[e2] = pk2(f[8 + 2 * e2] * rr * gq[2 + (e2 >> 1)][2 * (e2 & 1)], f[8 + 2 * e2 + 1] * rr * gq[2 + (e2 >> 1)][2 * (e2 & 1) + 1]); }
;           *(u32x4*)(qn + (size_t)t * 256 + 16 * l16) = o0; *(u32x4*)(qn + (size_t)t * 256 + 16 * l16 + 8) = o1; }
;         { float f[8]; float ss = 0.f;
; #pragma unroll
;           for (int e2 = 0; e2 < 4; ++e2) { f[2 * e2] = __uint_as_float(k0[e2] << 16); f[2 * e2 + 1] = __uint_as_float(k0[e2] & 0xffff0000u); }
; #pragma unroll
;           for (int e2 = 0; e2 < 8; ++e2) ss += f[e2] * f[e2];
;           const float rr = __builtin_amdgcn_rsqf(sum16(ss) * (1.0f / 128.0f) + EPS);
.LBB0_302:
	v_ashrrev_i32_e32 v39, 31, v38
	v_lshlrev_b64 v[44:45], 12, v[38:39]
	v_lshl_add_u64 v[44:45], s[60:61], 0, v[44:45]
	v_lshl_add_u64 v[56:57], v[44:45], 0, v[160:161]
	global_load_dwordx4 v[52:55], v[56:57], off offset:3072
	s_nop 0
	global_load_dwordx4 v[56:59], v[56:57], off offset:3088
	v_mov_b32_e32 v41, v161
	v_lshl_add_u64 v[60:61], v[44:45], 0, v[40:41]
	global_load_dwordx4 v[60:63], v[60:61], off offset:3584
	v_mov_b32_e32 v43, v161
	v_lshl_add_u64 v[44:45], v[44:45], 0, v[42:43]
	global_load_dwordx2 v[44:45], v[44:45], off offset:3840
	v_lshlrev_b64 v[68:69], 7, v[38:39]
	v_lshl_add_u64 v[64:65], v[28:29], 0, v[68:69]
	v_lshl_add_u64 v[68:69], v[30:31], 0, v[68:69]
	global_load_dwordx4 v[64:67], v[64:65], off
	s_waitcnt vmcnt(4)
	v_lshlrev_b32_e32 v94, 16, v52
	v_and_b32_e32 v95, 0xffff0000, v52
	v_lshlrev_b32_e32 v88, 16, v53
	v_and_b32_e32 v89, 0xffff0000, v53
	v_pk_mul_f32 v[52:53], v[94:95], v[94:95]
	v_pk_mul_f32 v[90:91], v[88:89], v[88:89]
	v_add_f32_e32 v41, v52, v53
	v_lshlrev_b32_e32 v82, 16, v54
	v_and_b32_e32 v83, 0xffff0000, v54
	v_add_f32_e32 v41, v90, v41
	v_lshlrev_b32_e32 v76, 16, v55
	v_and_b32_e32 v77, 0xffff0000, v55
	v_pk_mul_f32 v[54:55], v[82:83], v[82:83]
	v_add_f32_e32 v41, v91, v41
	v_add_f32_e32 v41, v54, v41
	v_pk_mul_f32 v[78:79], v[76:77], v[76:77]
	v_add_f32_e32 v41, v55, v41
	s_waitcnt vmcnt(3)
	v_lshlrev_b32_e32 v92, 16, v56
	v_and_b32_e32 v93, 0xffff0000, v56
	v_add_f32_e32 v41, v78, v41
	v_lshlrev_b32_e32 v84, 16, v57
	v_and_b32_e32 v85, 0xffff0000, v57
	v_pk_mul_f32 v[56:57], v[92:93], v[92:93]
	v_add_f32_e32 v41, v79, v41
	v_add_f32_e32 v41, v56, v41
	v_pk_mul_f32 v[86:87], v[84:85], v[84:85]
	v_add_f32_e32 v41, v57, v41
	v_lshlrev_b32_e32 v80, 16, v58
	v_and_b32_e32 v81, 0xffff0000, v58
	v_add_f32_e32 v41, v86, v41
	v_lshlrev_b32_e32 v72, 16, v59
	v_and_b32_e32 v73, 0xffff0000, v59
	v_pk_mul_f32 v[58:59], v[80:81], v[80:81]
	v_add_f32_e32 v41, v87, v41
	v_add_f32_e32 v41, v58, v41
	v_pk_mul_f32 v[74:75], v[72:73], v[72:73]
	v_add_f32_e32 v41, v59, v41
	v_add_f32_e32 v41, v74, v41
	v_add_f32_e32 v41, v75, v41
	global_load_dwordx4 v[68:71], v[68:69], off
	s_nop 1
	v_add_f32_dpp v41, v41, v41 quad_perm:[1,0,3,2] row_mask:0xf bank_mask:0xf
	s_nop 1
	v_add_f32_dpp v41, v41, v41 quad_perm:[2,3,0,1] row_mask:0xf bank_mask:0xf
	s_nop 1
	v_add_f32_dpp v41, v41, v41 row_half_mirror row_mask:0xf bank_mask:0xf
	s_nop 1
	v_add_f32_dpp v41, v41, v41 row_mirror row_mask:0xf bank_mask:0xf
	s_waitcnt lgkmcnt(0)
	v_fmamk_f32 v41, v41, 0x3b800000, v199
	v_rsq_f32_e32 v74, v41
	s_nop 0
	v_pk_mul_f32 v[54:55], v[74:75], v[92:93] op_sel_hi:[0,1]
	v_pk_mul_f32 v[54:55], v[20:21], v[54:55]
	v_pk_mul_f32 v[52:53], v[74:75], v[94:95] op_sel_hi:[0,1]
	v_cvt_pk_bf16_f32 v56, v54, v55
	v_pk_mul_f32 v[54:55], v[74:75], v[88:89] op_sel_hi:[0,1]
	v_pk_mul_f32 v[52:53], v[12:13], v[52:53]
	v_pk_mul_f32 v[54:55], v[14:15], v[54:55]
	v_cvt_pk_bf16_f32 v52, v52, v53
	v_cvt_pk_bf16_f32 v53, v54, v55
	v_pk_mul_f32 v[54:55], v[74:75], v[84:85] op_sel_hi:[0,1]
	v_pk_mul_f32 v[54:55], v[22:23], v[54:55]
	v_pk_mul_f32 v[58:59], v[74:75], v[80:81] op_sel_hi:[0,1]
	v_pk_mul_f32 v[72:73], v[74:75], v[72:73] op_sel_hi:[0,1]
	v_cvt_pk_bf16_f32 v57, v54, v55
	v_pk_mul_f32 v[54:55], v[74:75], v[82:83] op_sel_hi:[0,1]
	v_pk_mul_f32 v[58:59], v[24:25], v[58:59]
	v_pk_mul_f32 v[76:77], v[74:75], v[76:77] op_sel_hi:[0,1]
	v_pk_mul_f32 v[72:73], v[26:27], v[72:73]
	v_pk_mul_f32 v[54:55], v[16:17], v[54:55]
	v_cvt_pk_bf16_f32 v58, v58, v59
	v_pk_mul_f32 v[76:77], v[18:19], v[76:77]
	v_cvt_pk_bf16_f32 v59, v72, v73
	v_lshlrev_b64 v[72:73], 9, v[38:39]
	v_cvt_pk_bf16_f32 v54, v54, v55
	v_cvt_pk_bf16_f32 v55, v76, v77
	v_lshl_add_u64 v[72:73], v[32:33], 0, v[72:73]
	s_waitcnt vmcnt(3)
	v_lshlrev_b32_e32 v74, 16, v60
	v_and_b32_e32 v75, 0xffff0000, v60
	global_store_dwordx4 v[72:73], v[52:55], off
	global_store_dwordx4 v[72:73], v[56:59], off offset:16
	s_nop 0
	v_lshlrev_b32_e32 v54, 16, v62
	v_lshlrev_b32_e32 v56, 16, v63
	v_and_b32_e32 v57, 0xffff0000, v63
	v_and_b32_e32 v55, 0xffff0000, v62
	v_lshlrev_b32_e32 v62, 16, v61
	v_and_b32_e32 v63, 0xffff0000, v61
	v_pk_mul_f32 v[60:61], v[74:75], v[74:75]
	v_pk_mul_f32 v[72:73], v[62:63], v[62:63]
	v_add_f32_e32 v41, v60, v61
	v_add_f32_e32 v41, v72, v41
	v_pk_mul_f32 v[58:59], v[54:55], v[54:55]
	v_add_f32_e32 v41, v73, v41
	v_add_f32_e32 v41, v58, v41
	v_pk_mul_f32 v[52:53], v[56:57], v[56:57]
	v_add_f32_e32 v41, v59, v41
	v_add_f32_e32 v41, v52, v41
	v_add_f32_e32 v41, v53, v41
	s_nop 1
	v_add_f32_dpp v41, v41, v41 quad_perm:[1,0,3,2] row_mask:0xf bank_mask:0xf
	s_nop 1
	v_add_f32_dpp v41, v41, v41 quad_perm:[2,3,0,1] row_mask:0xf bank_mask:0xf
	s_nop 1
	v_add_f32_dpp v41, v41, v41 row_half_mirror row_mask:0xf bank_mask:0xf
	s_nop 1
	v_add_f32_dpp v41, v41, v41 row_mirror row_mask:0xf bank_mask:0xf
	s_waitcnt lgkmcnt(0)
; __device__ __forceinline__ unsigned pk2(float lo, float hi) { const f32x2 v = {lo, hi}; return __builtin_bit_cast(unsigned, __builtin_convertvector(v, hwbf16x2)); }
; __device__ __forceinline__ float sum16(float v) { v += __shfl_xor(v, 1); v += __shfl_xor(v, 2); v += __shfl_xor(v, 4); v += __shfl_xor(v, 8); return v; }
; __device__ __forceinline__ void prep_tokens(const bf16_t* __restrict__ proj, bf16_t* __restrict__ qn, bf16_t* __restrict__ kvn, bf16_t* __restrict__ Kb, const float* __restrict__ qa, const float* __restrict__ kva, const float* __restrict__ kr, ...
;     ...
;           const float rr = __builtin_amdgcn_rsqf(sum16(ss) * (1.0f / 128.0f) + EPS);
;           u32x4 o0;
; #pragma unroll
;           for (int e2 = 0; e2 < 4; ++e2) o0[e2] = pk2(f[2 * e2] * rr * gkv[e2 >> 1][2 * (e2 & 1)], f[2 * e2 + 1] * rr * gkv[e2 >> 1][2 * (e2 & 1) + 1]);
;           *(u32x4*)(kvn + (size_t)t * 128 + 8 * l16) = o0; }
;         { float y[4] = {__uint_as_float(p0[0] << 16), __uint_as_float(p0[0] & 0xffff0000u), __uint_as_float(p0[1] << 16), __uint_as_float(p0[1] & 0xffff0000u)};
;           const float rr = __builtin_amdgcn_rsqf(sum16((y[0] * y[0] + y[1] * y[1]) + (y[2] * y[2] + y[3] * y[3])) * (1.0f / 64.0f) + EPS);
;           float ov[4];
; #pragma unroll
;           for (int i = 0; i < 4; ++i) { y[i] = y[i] * rr * gr[i]; const float pn = __shfl_xor(y[i], 8);
;               ov[i] = l16 < 8 ? y[i] * c4[i] - pn * s4[i] : y[i] * c4[i] + pn * s4[i]; }
;           u32x2 w; w.x = pk2(ov[0], ov[1]); w.y = pk2(ov[2], ov[3]);
;           const int b = t >> 13, sp = t & 8191;
; #pragma unroll
;           for (int h = 0; h < 4; ++h) *(u32x2*)(Kb + ((size_t)(b * 4 + h) * SEQ + sp) * 192 + 128 + 4 * l16) = w; }
	v_fmamk_f32 v41, v41, 0x3c000000, v199
	v_rsq_f32_e32 v58, v41
	s_nop 0
	v_pk_mul_f32 v[54:55], v[58:59], v[54:55] op_sel_hi:[0,1]
	v_pk_mul_f32 v[56:57], v[58:59], v[56:57] op_sel_hi:[0,1]
	v_pk_mul_f32 v[52:53], v[58:59], v[74:75] op_sel_hi:[0,1]
	v_pk_mul_f32 v[60:61], v[58:59], v[62:63] op_sel_hi:[0,1]
	v_pk_mul_f32 v[54:55], v[8:9], v[54:55]
	v_pk_mul_f32 v[56:57], v[10:11], v[56:57]
	v_pk_mul_f32 v[52:53], v[4:5], v[52:53]
	v_pk_mul_f32 v[60:61], v[6:7], v[60:61]
	v_cvt_pk_bf16_f32 v54, v54, v55
	v_cvt_pk_bf16_f32 v55, v56, v57
	v_lshlrev_b64 v[56:57], 8, v[38:39]
	v_cvt_pk_bf16_f32 v52, v52, v53
	v_cvt_pk_bf16_f32 v53, v60, v61
	v_lshl_add_u64 v[56:57], v[34:35], 0, v[56:57]
	global_store_dwordx4 v[56:57], v[52:55], off
	s_waitcnt vmcnt(5)
	s_nop 0
	v_and_b32_e32 v53, 0xffff0000, v45
	v_and_b32_e32 v55, 0xffff0000, v44
	v_lshlrev_b32_e32 v52, 16, v45
	v_lshlrev_b32_e32 v54, 16, v44
	v_mov_b32_e32 v56, v55
	v_mov_b32_e32 v57, v53
	v_mov_b32_e32 v44, v54
	v_mov_b32_e32 v45, v52
	v_pk_mul_f32 v[56:57], v[56:57], v[56:57]
	s_nop 0
	v_pk_fma_f32 v[44:45], v[44:45], v[44:45], v[56:57]
	s_nop 0
	v_add_f32_e32 v39, v44, v45
	s_nop 1
	v_add_f32_dpp v39, v39, v39 quad_perm:[1,0,3,2] row_mask:0xf bank_mask:0xf
	s_nop 1
	v_add_f32_dpp v39, v39, v39 quad_perm:[2,3,0,1] row_mask:0xf bank_mask:0xf
	s_nop 1
	v_add_f32_dpp v39, v39, v39 row_half_mirror row_mask:0xf bank_mask:0xf
	s_nop 1
	v_add_f32_dpp v39, v39, v39 row_mirror row_mask:0xf bank_mask:0xf
	s_waitcnt lgkmcnt(0)
	v_fmamk_f32 v39, v39, 0x3c800000, v199
	v_rsq_f32_e32 v44, v39
	v_ashrrev_i32_e32 v41, 9, v46
	v_and_b32_e32 v39, 0x1fff, v38
	v_add_u32_e32 v38, 0x2000, v38
	v_pk_mul_f32 v[54:55], v[44:45], v[54:55] op_sel_hi:[0,1]
	v_pk_mul_f32 v[44:45], v[44:45], v[52:53] op_sel_hi:[0,1]
	v_pk_mul_f32 v[44:45], v[2:3], v[44:45]
	s_nop 1
	v_mov_b32_dpp v52, v44 row_ror:8 row_mask:0xf bank_mask:0xf
	s_nop 1
	v_mov_b32_dpp v53, v45 row_ror:8 row_mask:0xf bank_mask:0xf
	v_pk_mul_f32 v[54:55], v[0:1], v[54:55]
	s_nop 1
	v_mov_b32_dpp v56, v54 row_ror:8 row_mask:0xf bank_mask:0xf
	s_nop 1
	v_mov_b32_dpp v57, v55 row_ror:8 row_mask:0xf bank_mask:0xf
	s_waitcnt vmcnt(3) lgkmcnt(2)
	v_pk_mul_f32 v[52:53], v[70:71], v[52:53]
	s_nop 0
	v_cndmask_b32_e64 v53, v53, -v53, vcc
	v_cndmask_b32_e64 v52, v52, -v52, vcc
	s_waitcnt lgkmcnt(0)
	v_pk_mul_f32 v[56:57], v[68:69], v[56:57]
	v_pk_fma_f32 v[52:53], v[66:67], v[44:45], v[52:53]
	v_cndmask_b32_e64 v57, v57, -v57, vcc
	v_cndmask_b32_e64 v56, v56, -v56, vcc
	v_cvt_pk_bf16_f32 v45, v52, v53
	v_and_b32_e32 v52, -4, v41
	v_pk_fma_f32 v[54:55], v[64:65], v[54:55], v[56:57]
	v_ashrrev_i32_e32 v53, 31, v52
	v_cvt_pk_bf16_f32 v44, v54, v55
	v_lshlrev_b64 v[54:55], 13, v[52:53]
	v_or_b32_e32 v43, v54, v39
	v_mad_u64_u32 v[56:57], s[0:1], v43, s67, v[36:37]
	v_or_b32_e32 v54, 1, v52
	v_mad_i32_i24 v57, v55, s67, v57
	v_ashrrev_i32_e32 v55, 31, v54
	v_or_b32_e32 v52, 2, v52
	v_lshlrev_b64 v[54:55], 13, v[54:55]
	v_ashrrev_i32_e32 v53, 31, v52
	v_or_b32_e32 v43, v54, v39
	v_lshlrev_b64 v[52:53], 13, v[52:53]
	global_store_dwordx2 v[56:57], v[44:45], off offset:256
	v_mad_u64_u32 v[56:57], s[0:1], v43, s67, v[36:37]
	v_or_b32_e32 v43, v52, v39
	v_mad_i32_i24 v57, v55, s67, v57
	v_mad_u64_u32 v[54:55], s[0:1], v43, s67, v[36:37]
	v_or_b32_e32 v52, 3, v41
	v_mad_i32_i24 v55, v53, s67, v55
	v_ashrrev_i32_e32 v53, 31, v52
	v_lshlrev_b64 v[52:53], 13, v[52:53]
	v_or_b32_e32 v39, v52, v39
	global_store_dwordx2 v[54:55], v[44:45], off offset:256
	v_mad_u64_u32 v[54:55], s[0:1], v39, s67, v[36:37]
	s_movk_i32 s0, 0x17ff
	v_add_u32_e32 v39, 0x800, v46
	v_cmp_lt_i32_e64 s[0:1], s0, v46
	v_mad_i32_i24 v55, v53, s67, v55
	s_or_b64 s[4:5], s[0:1], s[4:5]
	v_mov_b32_e32 v46, v39
	global_store_dwordx2 v[56:57], v[44:45], off offset:256
	global_store_dwordx2 v[54:55], v[44:45], off offset:256
	s_andn2_b64 exec, exec, s[4:5]
	s_cbranch_execnz .LBB0_302
